# Resid/out-proj GEMM K-loop: LDS-DMA loads issued at the start of each load segment (latency-bound A stream gets more time in flight)
# speedup vs baseline: 1.0028x; 1.0028x over previous
; #define PG8_STAGE(bufoff, gbase, voff) do { _Pragma("unroll") for (int _i = 0; _i < 2; ++_i) \
;         __builtin_amdgcn_global_load_lds((const unsigned*)((const char*)(gbase) + (voff)[_i]), (PG8_LAS unsigned*)(lds + (bufoff) + ldsw + _i * 8192), 16, 0, 0); } while (0)
; #define PG8_LDA(dst, b, h) do { _Pragma("unroll") for (int m = 0; m < 4; ++m) _Pragma("unroll") for (int k = 0; k < 2; ++k) dst[m][k] = *(const PG8_LAS bf16x8*)(lds + PG8_SA(b, h) + aoff + m * 2048 + k * 1024); } while (0)
; #define PG8_LDB(dst, b, h) do { _Pragma("unroll") for (int n = 0; n < 2; ++n) _Pragma("unroll") for (int k = 0; k < 2; ++k) dst[n][k] = *(const PG8_LAS bf16x8*)(lds + PG8_SB(b, h) + boff + n * 2048 + k * 1024); } while (0)
; #define PG8_MMA(ai, bj, At, Bt) do { __builtin_amdgcn_s_setprio(1); _Pragma("unroll") for (int m = 0; m < 4; ++m) _Pragma("unroll") for (int n = 0; n < 2; ++n) _Pragma("unroll") for (int k = 0; k < 2; ++k) \
;         acc[ai][bj][m][n] = __builtin_amdgcn_mfma_f32_16x16x32_bf16(Bt[n][k], At[m][k], acc[ai][bj][m][n], 0, 0, 0); __builtin_amdgcn_s_setprio(0); } while (0)
; #define PG8_WAIT_V(n) asm volatile("s_waitcnt vmcnt(" #n ")" ::: "memory")
; #define PG8_WAIT_L(n) asm volatile("s_waitcnt lgkmcnt(" #n ")" ::: "memory")
; #define PG8_BAR __builtin_amdgcn_s_barrier()
; #define PG8_SCHED __builtin_amdgcn_sched_barrier(0)
; template <class Epi, class Sched, bool ALIGN_EPI = false, bool SP2 = false>
; __device__ __forceinline__ void gemm_phase(PG8_LAS unsigned char* lds, const Gemm g, const Sched& S, const Epi& E) {
;     ...
;             PG8_LDB(B0, 0, 0); PG8_LDB(B1, 0, 1); PG8_SCHED; PG8_LDA(At, 0, 0); PG8_STAGE(PG8_SA(1, 1), a1 + hstep, voffA);
;             PG8_WAIT_V(8); PG8_WAIT_L(0); PG8_BAR; PG8_MMA(0, 0, At, B0); PG8_MMA(0, 1, At, B1); PG8_BAR; PG8_SCHED;
;             PG8_LDA(At, 0, 1); PG8_STAGE(PG8_SB(0, 0), b2, voffB); PG8_STAGE(PG8_SB(0, 1), b2 + hstep, voffB); PG8_STAGE(PG8_SA(0, 0), a2, voffA);
;             PG8_WAIT_V(8); PG8_WAIT_L(0); PG8_BAR; PG8_MMA(1, 0, At, B0); PG8_MMA(1, 1, At, B1); PG8_BAR; PG8_SCHED;
.Lz_enter_568:
	s_add_u32 s10, s62, 0x80
	s_addc_u32 s11, s63, 0
	s_add_u32 s62, s20, 0x100
	s_addc_u32 s63, s21, 0
	s_mov_b32 s20, 0
	s_add_i32 m0, s64, 0xc000
	ds_read_b128 v[82:85], v246
	global_load_lds_dwordx4 v224, s[10:11]
	s_add_i32 m0, s64, 0xe000
	ds_read_b128 v[98:101], v246 offset:1024
	global_load_lds_dwordx4 v226, s[10:11]
	ds_read_b128 v[102:105], v246 offset:2048
	ds_read_b128 v[106:109], v246 offset:3072
	ds_read_b128 v[146:149], v246 offset:16384
	ds_read_b128 v[150:153], v246 offset:17408
	ds_read_b128 v[154:157], v246 offset:18432
	ds_read_b128 v[158:161], v246 offset:19456
	ds_read_b128 v[162:165], v249
	ds_read_b128 v[166:169], v249 offset:1024
	ds_read_b128 v[170:173], v249 offset:2048
	ds_read_b128 v[174:177], v249 offset:3072
	ds_read_b128 v[178:181], v249 offset:4096
	ds_read_b128 v[182:185], v249 offset:5120
	ds_read_b128 v[186:189], v249 offset:6144
	ds_read_b128 v[190:193], v249 offset:7168
	s_waitcnt vmcnt(8) lgkmcnt(0)
	s_barrier
	s_setprio 1
	v_mfma_f32_16x16x32_bf16 v[142:145], v[82:85], v[162:165], 0
	v_mfma_f32_16x16x32_bf16 v[138:141], v[102:105], v[162:165], 0
	v_mfma_f32_16x16x32_bf16 v[126:129], v[82:85], v[170:173], 0
	v_mfma_f32_16x16x32_bf16 v[122:125], v[102:105], v[170:173], 0
	s_add_i32 s78, s20, 2
	v_mfma_f32_16x16x32_bf16 v[110:113], v[82:85], v[178:181], 0
	s_add_u32 s79, s10, 0x80
	v_mfma_f32_16x16x32_bf16 v[94:97], v[102:105], v[178:181], 0
	s_addc_u32 s21, s11, 0
	v_mfma_f32_16x16x32_bf16 v[78:81], v[82:85], v[186:189], 0
	s_cmp_eq_u32 s68, s20
	v_mfma_f32_16x16x32_bf16 v[74:77], v[102:105], v[186:189], 0
	s_cselect_b32 s21, s59, s21
	v_mfma_f32_16x16x32_bf16 v[142:145], v[98:101], v[166:169], v[142:145]
	s_cselect_b32 s20, s58, s79
	v_mfma_f32_16x16x32_bf16 v[138:141], v[106:109], v[166:169], v[138:141]
	s_cselect_b32 s81, s61, s63
	v_mfma_f32_16x16x32_bf16 v[126:129], v[98:101], v[174:177], v[126:129]
	s_cselect_b32 s80, s60, s62
	v_mfma_f32_16x16x32_bf16 v[122:125], v[106:109], v[174:177], v[122:125]
	v_mfma_f32_16x16x32_bf16 v[110:113], v[98:101], v[182:185], v[110:113]
	v_mfma_f32_16x16x32_bf16 v[94:97], v[106:109], v[182:185], v[94:97]
	v_mfma_f32_16x16x32_bf16 v[78:81], v[98:101], v[190:193], v[78:81]
	v_mfma_f32_16x16x32_bf16 v[74:77], v[106:109], v[190:193], v[74:77]
	v_mfma_f32_16x16x32_bf16 v[134:137], v[146:149], v[162:165], 0
	v_mfma_f32_16x16x32_bf16 v[130:133], v[154:157], v[162:165], 0
	v_mfma_f32_16x16x32_bf16 v[118:121], v[146:149], v[170:173], 0
	v_mfma_f32_16x16x32_bf16 v[114:117], v[154:157], v[170:173], 0
	v_mfma_f32_16x16x32_bf16 v[90:93], v[146:149], v[178:181], 0
	v_mfma_f32_16x16x32_bf16 v[86:89], v[154:157], v[178:181], 0
	v_mfma_f32_16x16x32_bf16 v[70:73], v[146:149], v[186:189], 0
	v_mfma_f32_16x16x32_bf16 v[66:69], v[154:157], v[186:189], 0
	v_mfma_f32_16x16x32_bf16 v[134:137], v[150:153], v[166:169], v[134:137]
	v_mfma_f32_16x16x32_bf16 v[130:133], v[158:161], v[166:169], v[130:133]
	v_mfma_f32_16x16x32_bf16 v[118:121], v[150:153], v[174:177], v[118:121]
	v_mfma_f32_16x16x32_bf16 v[114:117], v[158:161], v[174:177], v[114:117]
	v_mfma_f32_16x16x32_bf16 v[90:93], v[150:153], v[182:185], v[90:93]
	v_mfma_f32_16x16x32_bf16 v[86:89], v[158:161], v[182:185], v[86:89]
	v_mfma_f32_16x16x32_bf16 v[70:73], v[150:153], v[190:193], v[70:73]
	v_mfma_f32_16x16x32_bf16 v[66:69], v[158:161], v[190:193], v[66:69]
	s_setprio 0
	s_barrier
	s_add_u32 s100, s80, s46
	s_addc_u32 s101, s81, s47
	s_add_i32 m0, s22, 0x10000
	ds_read_b128 v[162:165], v249 offset:16384
	global_load_lds_dwordx4 v0, s[80:81]
	s_add_i32 m0, s22, 0x12000
	ds_read_b128 v[166:169], v249 offset:17408
	global_load_lds_dwordx4 v218, s[80:81]
	s_add_i32 m0, s22, 0x14000
	ds_read_b128 v[170:173], v249 offset:18432
	global_load_lds_dwordx4 v0, s[100:101]
	s_add_i32 m0, s22, 0x16000
	ds_read_b128 v[174:177], v249 offset:19456
	global_load_lds_dwordx4 v218, s[100:101]
	s_mov_b32 m0, s64
	ds_read_b128 v[178:181], v249 offset:20480
	global_load_lds_dwordx4 v0, s[20:21]
	s_mov_b32 m0, s30
	ds_read_b128 v[182:185], v249 offset:21504
	global_load_lds_dwordx4 v218, s[20:21]
	ds_read_b128 v[186:189], v249 offset:22528
	ds_read_b128 v[190:193], v249 offset:23552
	s_waitcnt vmcnt(8) lgkmcnt(0)
	s_barrier
	s_setprio 1
	v_mfma_f32_16x16x32_bf16 v[62:65], v[82:85], v[162:165], 0
	v_mfma_f32_16x16x32_bf16 v[58:61], v[102:105], v[162:165], 0
	v_mfma_f32_16x16x32_bf16 v[46:49], v[82:85], v[170:173], 0
	v_mfma_f32_16x16x32_bf16 v[42:45], v[102:105], v[170:173], 0
	v_mfma_f32_16x16x32_bf16 v[30:33], v[82:85], v[178:181], 0
	v_mfma_f32_16x16x32_bf16 v[26:29], v[102:105], v[178:181], 0
	v_mfma_f32_16x16x32_bf16 v[14:17], v[82:85], v[186:189], 0
	v_mfma_f32_16x16x32_bf16 v[10:13], v[102:105], v[186:189], 0
	v_mfma_f32_16x16x32_bf16 v[62:65], v[98:101], v[166:169], v[62:65]
	v_mfma_f32_16x16x32_bf16 v[58:61], v[106:109], v[166:169], v[58:61]
	v_mfma_f32_16x16x32_bf16 v[46:49], v[98:101], v[174:177], v[46:49]
	v_mfma_f32_16x16x32_bf16 v[42:45], v[106:109], v[174:177], v[42:45]
	v_mfma_f32_16x16x32_bf16 v[30:33], v[98:101], v[182:185], v[30:33]
	v_mfma_f32_16x16x32_bf16 v[26:29], v[106:109], v[182:185], v[26:29]
	v_mfma_f32_16x16x32_bf16 v[14:17], v[98:101], v[190:193], v[14:17]
	v_mfma_f32_16x16x32_bf16 v[10:13], v[106:109], v[190:193], v[10:13]
	v_mfma_f32_16x16x32_bf16 v[54:57], v[146:149], v[162:165], 0
	v_mfma_f32_16x16x32_bf16 v[50:53], v[154:157], v[162:165], 0
	v_mfma_f32_16x16x32_bf16 v[38:41], v[146:149], v[170:173], 0
	v_mfma_f32_16x16x32_bf16 v[34:37], v[154:157], v[170:173], 0
	v_mfma_f32_16x16x32_bf16 v[22:25], v[146:149], v[178:181], 0
	v_mfma_f32_16x16x32_bf16 v[18:21], v[154:157], v[178:181], 0
	v_mfma_f32_16x16x32_bf16 v[6:9], v[146:149], v[186:189], 0
	v_mfma_f32_16x16x32_bf16 v[2:5], v[154:157], v[186:189], 0
	v_mfma_f32_16x16x32_bf16 v[54:57], v[150:153], v[166:169], v[54:57]
	v_mfma_f32_16x16x32_bf16 v[50:53], v[158:161], v[166:169], v[50:53]
	v_mfma_f32_16x16x32_bf16 v[38:41], v[150:153], v[174:177], v[38:41]
	v_mfma_f32_16x16x32_bf16 v[34:37], v[158:161], v[174:177], v[34:37]
	v_mfma_f32_16x16x32_bf16 v[22:25], v[150:153], v[182:185], v[22:25]
	v_mfma_f32_16x16x32_bf16 v[18:21], v[158:161], v[182:185], v[18:21]
	v_mfma_f32_16x16x32_bf16 v[6:9], v[150:153], v[190:193], v[6:9]
	v_mfma_f32_16x16x32_bf16 v[2:5], v[158:161], v[190:193], v[2:5]
	s_setprio 0
	s_barrier
; #define PG8_STAGE(bufoff, gbase, voff) do { _Pragma("unroll") for (int _i = 0; _i < 2; ++_i) \
;         __builtin_amdgcn_global_load_lds((const unsigned*)((const char*)(gbase) + (voff)[_i]), (PG8_LAS unsigned*)(lds + (bufoff) + ldsw + _i * 8192), 16, 0, 0); } while (0)
; #define PG8_LDA(dst, b, h) do { _Pragma("unroll") for (int m = 0; m < 4; ++m) _Pragma("unroll") for (int k = 0; k < 2; ++k) dst[m][k] = *(const PG8_LAS bf16x8*)(lds + PG8_SA(b, h) + aoff + m * 2048 + k * 1024); } while (0)
; #define PG8_LDB(dst, b, h) do { _Pragma("unroll") for (int n = 0; n < 2; ++n) _Pragma("unroll") for (int k = 0; k < 2; ++k) dst[n][k] = *(const PG8_LAS bf16x8*)(lds + PG8_SB(b, h) + boff + n * 2048 + k * 1024); } while (0)
; #define PG8_MMA(ai, bj, At, Bt) do { __builtin_amdgcn_s_setprio(1); _Pragma("unroll") for (int m = 0; m < 4; ++m) _Pragma("unroll") for (int n = 0; n < 2; ++n) _Pragma("unroll") for (int k = 0; k < 2; ++k) \
;         acc[ai][bj][m][n] = __builtin_amdgcn_mfma_f32_16x16x32_bf16(Bt[n][k], At[m][k], acc[ai][bj][m][n], 0, 0, 0); __builtin_amdgcn_s_setprio(0); } while (0)
; #define PG8_WAIT_V(n) asm volatile("s_waitcnt vmcnt(" #n ")" ::: "memory")
; #define PG8_WAIT_L(n) asm volatile("s_waitcnt lgkmcnt(" #n ")" ::: "memory")
; #define PG8_BAR __builtin_amdgcn_s_barrier()
; #define PG8_SCHED __builtin_amdgcn_sched_barrier(0)
; template <class Epi, class Sched, bool ALIGN_EPI = false, bool SP2 = false>
; __device__ __forceinline__ void gemm_phase(PG8_LAS unsigned char* lds, const Gemm g, const Sched& S, const Epi& E) {
;     ...
;             PG8_LDB(B0, 1, 0); PG8_LDB(B1, 1, 1); PG8_SCHED; PG8_LDA(At, 1, 0); PG8_STAGE(PG8_SA(0, 1), a2 + hstep, voffA);
;             PG8_WAIT_V(8); PG8_WAIT_L(0); PG8_BAR; PG8_MMA(0, 0, At, B0); PG8_MMA(0, 1, At, B1); PG8_BAR; PG8_SCHED;
;             PG8_LDA(At, 1, 1); PG8_STAGE(PG8_SB(1, 0), b3, voffB); PG8_STAGE(PG8_SB(1, 1), b3 + hstep, voffB); PG8_STAGE(PG8_SA(1, 0), a3, voffA);
;             PG8_WAIT_V(8); PG8_WAIT_L(0); PG8_BAR; PG8_MMA(1, 0, At, B0); PG8_MMA(1, 1, At, B1); PG8_BAR; PG8_SCHED;
	s_mov_b32 m0, s31
	ds_read_b128 v[82:85], v246 offset:32768
	global_load_lds_dwordx4 v224, s[20:21]
	s_mov_b32 m0, s33
	ds_read_b128 v[98:101], v246 offset:33792
	global_load_lds_dwordx4 v226, s[20:21]
	ds_read_b128 v[102:105], v246 offset:34816
	ds_read_b128 v[106:109], v246 offset:35840
	ds_read_b128 v[146:149], v246 offset:49152
	ds_read_b128 v[150:153], v246 offset:50176
	ds_read_b128 v[154:157], v246 offset:51200
	ds_read_b128 v[158:161], v246 offset:52224
	ds_read_b128 v[162:165], v249 offset:32768
	ds_read_b128 v[166:169], v249 offset:33792
	ds_read_b128 v[170:173], v249 offset:34816
	ds_read_b128 v[174:177], v249 offset:35840
	ds_read_b128 v[178:181], v249 offset:36864
	ds_read_b128 v[182:185], v249 offset:37888
	ds_read_b128 v[186:189], v249 offset:38912
	ds_read_b128 v[190:193], v249 offset:39936
	s_waitcnt vmcnt(8) lgkmcnt(0)
	s_barrier
	s_setprio 1
	v_mfma_f32_16x16x32_bf16 v[142:145], v[82:85], v[162:165], v[142:145]
	v_mfma_f32_16x16x32_bf16 v[138:141], v[102:105], v[162:165], v[138:141]
	v_mfma_f32_16x16x32_bf16 v[126:129], v[82:85], v[170:173], v[126:129]
	v_mfma_f32_16x16x32_bf16 v[122:125], v[102:105], v[170:173], v[122:125]
	v_mfma_f32_16x16x32_bf16 v[110:113], v[82:85], v[178:181], v[110:113]
	v_mfma_f32_16x16x32_bf16 v[94:97], v[102:105], v[178:181], v[94:97]
	v_mfma_f32_16x16x32_bf16 v[78:81], v[82:85], v[186:189], v[78:81]
	v_mfma_f32_16x16x32_bf16 v[74:77], v[102:105], v[186:189], v[74:77]
	v_mfma_f32_16x16x32_bf16 v[142:145], v[98:101], v[166:169], v[142:145]
	v_mfma_f32_16x16x32_bf16 v[138:141], v[106:109], v[166:169], v[138:141]
	v_mfma_f32_16x16x32_bf16 v[126:129], v[98:101], v[174:177], v[126:129]
	v_mfma_f32_16x16x32_bf16 v[122:125], v[106:109], v[174:177], v[122:125]
	v_mfma_f32_16x16x32_bf16 v[110:113], v[98:101], v[182:185], v[110:113]
	v_mfma_f32_16x16x32_bf16 v[94:97], v[106:109], v[182:185], v[94:97]
	v_mfma_f32_16x16x32_bf16 v[78:81], v[98:101], v[190:193], v[78:81]
	v_mfma_f32_16x16x32_bf16 v[74:77], v[106:109], v[190:193], v[74:77]
	v_mfma_f32_16x16x32_bf16 v[134:137], v[146:149], v[162:165], v[134:137]
	v_mfma_f32_16x16x32_bf16 v[130:133], v[154:157], v[162:165], v[130:133]
	v_mfma_f32_16x16x32_bf16 v[118:121], v[146:149], v[170:173], v[118:121]
	v_mfma_f32_16x16x32_bf16 v[114:117], v[154:157], v[170:173], v[114:117]
	v_mfma_f32_16x16x32_bf16 v[90:93], v[146:149], v[178:181], v[90:93]
	v_mfma_f32_16x16x32_bf16 v[86:89], v[154:157], v[178:181], v[86:89]
	v_mfma_f32_16x16x32_bf16 v[70:73], v[146:149], v[186:189], v[70:73]
	v_mfma_f32_16x16x32_bf16 v[66:69], v[154:157], v[186:189], v[66:69]
	v_mfma_f32_16x16x32_bf16 v[134:137], v[150:153], v[166:169], v[134:137]
	v_mfma_f32_16x16x32_bf16 v[130:133], v[158:161], v[166:169], v[130:133]
	v_mfma_f32_16x16x32_bf16 v[118:121], v[150:153], v[174:177], v[118:121]
	v_mfma_f32_16x16x32_bf16 v[114:117], v[158:161], v[174:177], v[114:117]
	v_mfma_f32_16x16x32_bf16 v[90:93], v[150:153], v[182:185], v[90:93]
	v_mfma_f32_16x16x32_bf16 v[86:89], v[158:161], v[182:185], v[86:89]
	v_mfma_f32_16x16x32_bf16 v[70:73], v[150:153], v[190:193], v[70:73]
	v_mfma_f32_16x16x32_bf16 v[66:69], v[158:161], v[190:193], v[66:69]
	s_setprio 0
	s_barrier
	s_add_i32 m0, s22, 0x17f80
	ds_read_b128 v[162:165], v249 offset:49152
	global_load_lds_dwordx4 v0, s[80:81] offset:128
	s_add_i32 m0, s22, 0x19f80
	ds_read_b128 v[166:169], v249 offset:50176
	global_load_lds_dwordx4 v218, s[80:81] offset:128
	s_add_i32 m0, s22, 0x1bf80
	ds_read_b128 v[170:173], v249 offset:51200
	global_load_lds_dwordx4 v0, s[100:101] offset:128
	s_add_i32 m0, s22, 0x1df80
	ds_read_b128 v[174:177], v249 offset:52224
	global_load_lds_dwordx4 v218, s[100:101] offset:128
	s_sub_i32 m0, s39, 0x80
	ds_read_b128 v[178:181], v249 offset:53248
	global_load_lds_dwordx4 v0, s[20:21] offset:128
	s_sub_i32 m0, s65, 0x80
	ds_read_b128 v[182:185], v249 offset:54272
	global_load_lds_dwordx4 v218, s[20:21] offset:128
	ds_read_b128 v[186:189], v249 offset:55296
	ds_read_b128 v[190:193], v249 offset:56320
	s_waitcnt vmcnt(8) lgkmcnt(0)
	s_barrier
	s_setprio 1
	v_mfma_f32_16x16x32_bf16 v[62:65], v[82:85], v[162:165], v[62:65]
	v_mfma_f32_16x16x32_bf16 v[58:61], v[102:105], v[162:165], v[58:61]
	v_mfma_f32_16x16x32_bf16 v[46:49], v[82:85], v[170:173], v[46:49]
	v_mfma_f32_16x16x32_bf16 v[42:45], v[102:105], v[170:173], v[42:45]
	s_add_u32 s10, s10, 0x100
	v_mfma_f32_16x16x32_bf16 v[30:33], v[82:85], v[178:181], v[30:33]
	s_addc_u32 s11, s11, 0
	v_mfma_f32_16x16x32_bf16 v[26:29], v[102:105], v[178:181], v[26:29]
	s_add_u32 s62, s62, 0x100
	v_mfma_f32_16x16x32_bf16 v[14:17], v[82:85], v[186:189], v[14:17]
	s_addc_u32 s63, s63, 0
	v_mfma_f32_16x16x32_bf16 v[10:13], v[102:105], v[186:189], v[10:13]
	s_mov_b32 s20, s78
	v_mfma_f32_16x16x32_bf16 v[62:65], v[98:101], v[166:169], v[62:65]
	v_mfma_f32_16x16x32_bf16 v[58:61], v[106:109], v[166:169], v[58:61]
	v_mfma_f32_16x16x32_bf16 v[46:49], v[98:101], v[174:177], v[46:49]
	v_mfma_f32_16x16x32_bf16 v[42:45], v[106:109], v[174:177], v[42:45]
	v_mfma_f32_16x16x32_bf16 v[30:33], v[98:101], v[182:185], v[30:33]
	v_mfma_f32_16x16x32_bf16 v[26:29], v[106:109], v[182:185], v[26:29]
	v_mfma_f32_16x16x32_bf16 v[14:17], v[98:101], v[190:193], v[14:17]
	v_mfma_f32_16x16x32_bf16 v[10:13], v[106:109], v[190:193], v[10:13]
	v_mfma_f32_16x16x32_bf16 v[54:57], v[146:149], v[162:165], v[54:57]
	v_mfma_f32_16x16x32_bf16 v[50:53], v[154:157], v[162:165], v[50:53]
	v_mfma_f32_16x16x32_bf16 v[38:41], v[146:149], v[170:173], v[38:41]
	v_mfma_f32_16x16x32_bf16 v[34:37], v[154:157], v[170:173], v[34:37]
	v_mfma_f32_16x16x32_bf16 v[22:25], v[146:149], v[178:181], v[22:25]
	v_mfma_f32_16x16x32_bf16 v[18:21], v[154:157], v[178:181], v[18:21]
	v_mfma_f32_16x16x32_bf16 v[6:9], v[146:149], v[186:189], v[6:9]
	v_mfma_f32_16x16x32_bf16 v[2:5], v[154:157], v[186:189], v[2:5]
	v_mfma_f32_16x16x32_bf16 v[54:57], v[150:153], v[166:169], v[54:57]
	v_mfma_f32_16x16x32_bf16 v[50:53], v[158:161], v[166:169], v[50:53]
	v_mfma_f32_16x16x32_bf16 v[38:41], v[150:153], v[174:177], v[38:41]
	v_mfma_f32_16x16x32_bf16 v[34:37], v[158:161], v[174:177], v[34:37]
	v_mfma_f32_16x16x32_bf16 v[22:25], v[150:153], v[182:185], v[22:25]
	v_mfma_f32_16x16x32_bf16 v[18:21], v[158:161], v[182:185], v[18:21]
	v_mfma_f32_16x16x32_bf16 v[6:9], v[150:153], v[190:193], v[6:9]
	v_mfma_f32_16x16x32_bf16 v[2:5], v[158:161], v[190:193], v[2:5]
	s_setprio 0
	s_barrier
	s_cmp_ge_i32 s78, s67
	s_cbranch_scc1 .Lpz_exit_570
; #define PG8_STAGE(bufoff, gbase, voff) do { _Pragma("unroll") for (int _i = 0; _i < 2; ++_i) \
;         __builtin_amdgcn_global_load_lds((const unsigned*)((const char*)(gbase) + (voff)[_i]), (PG8_LAS unsigned*)(lds + (bufoff) + ldsw + _i * 8192), 16, 0, 0); } while (0)
; #define PG8_LDA(dst, b, h) do { _Pragma("unroll") for (int m = 0; m < 4; ++m) _Pragma("unroll") for (int k = 0; k < 2; ++k) dst[m][k] = *(const PG8_LAS bf16x8*)(lds + PG8_SA(b, h) + aoff + m * 2048 + k * 1024); } while (0)
; #define PG8_LDB(dst, b, h) do { _Pragma("unroll") for (int n = 0; n < 2; ++n) _Pragma("unroll") for (int k = 0; k < 2; ++k) dst[n][k] = *(const PG8_LAS bf16x8*)(lds + PG8_SB(b, h) + boff + n * 2048 + k * 1024); } while (0)
; #define PG8_MMA(ai, bj, At, Bt) do { __builtin_amdgcn_s_setprio(1); _Pragma("unroll") for (int m = 0; m < 4; ++m) _Pragma("unroll") for (int n = 0; n < 2; ++n) _Pragma("unroll") for (int k = 0; k < 2; ++k) \
;         acc[ai][bj][m][n] = __builtin_amdgcn_mfma_f32_16x16x32_bf16(Bt[n][k], At[m][k], acc[ai][bj][m][n], 0, 0, 0); __builtin_amdgcn_s_setprio(0); } while (0)
; #define PG8_WAIT_V(n) asm volatile("s_waitcnt vmcnt(" #n ")" ::: "memory")
; #define PG8_WAIT_L(n) asm volatile("s_waitcnt lgkmcnt(" #n ")" ::: "memory")
; #define PG8_BAR __builtin_amdgcn_s_barrier()
; #define PG8_SCHED __builtin_amdgcn_sched_barrier(0)
; template <class Epi, class Sched, bool ALIGN_EPI = false, bool SP2 = false>
; __device__ __forceinline__ void gemm_phase(PG8_LAS unsigned char* lds, const Gemm g, const Sched& S, const Epi& E) {
;     ...
;             PG8_LDB(B0, 0, 0); PG8_LDB(B1, 0, 1); PG8_SCHED; PG8_LDA(At, 0, 0); PG8_STAGE(PG8_SA(1, 1), a1 + hstep, voffA);
;             PG8_WAIT_V(8); PG8_WAIT_L(0); PG8_BAR; PG8_MMA(0, 0, At, B0); PG8_MMA(0, 1, At, B1); PG8_BAR; PG8_SCHED;
;             PG8_LDA(At, 0, 1); PG8_STAGE(PG8_SB(0, 0), b2, voffB); PG8_STAGE(PG8_SB(0, 1), b2 + hstep, voffB); PG8_STAGE(PG8_SA(0, 0), a2, voffA);
;             PG8_WAIT_V(8); PG8_WAIT_L(0); PG8_BAR; PG8_MMA(1, 0, At, B0); PG8_MMA(1, 1, At, B1); PG8_BAR; PG8_SCHED;
.LBB0_570:
	s_add_i32 m0, s64, 0xc000
	ds_read_b128 v[82:85], v246
	global_load_lds_dwordx4 v224, s[10:11]
	s_add_i32 m0, s64, 0xe000
	ds_read_b128 v[98:101], v246 offset:1024
	global_load_lds_dwordx4 v226, s[10:11]
	ds_read_b128 v[102:105], v246 offset:2048
	ds_read_b128 v[106:109], v246 offset:3072
	ds_read_b128 v[146:149], v246 offset:16384
	ds_read_b128 v[150:153], v246 offset:17408
	ds_read_b128 v[154:157], v246 offset:18432
	ds_read_b128 v[158:161], v246 offset:19456
	ds_read_b128 v[162:165], v249
	ds_read_b128 v[166:169], v249 offset:1024
	ds_read_b128 v[170:173], v249 offset:2048
	ds_read_b128 v[174:177], v249 offset:3072
	ds_read_b128 v[178:181], v249 offset:4096
	ds_read_b128 v[182:185], v249 offset:5120
	ds_read_b128 v[186:189], v249 offset:6144
	ds_read_b128 v[190:193], v249 offset:7168
	s_waitcnt vmcnt(8) lgkmcnt(0)
	s_barrier
	s_setprio 1
	v_mfma_f32_16x16x32_bf16 v[142:145], v[82:85], v[162:165], v[142:145]
	v_mfma_f32_16x16x32_bf16 v[138:141], v[102:105], v[162:165], v[138:141]
	v_mfma_f32_16x16x32_bf16 v[126:129], v[82:85], v[170:173], v[126:129]
	v_mfma_f32_16x16x32_bf16 v[122:125], v[102:105], v[170:173], v[122:125]
	s_add_i32 s78, s20, 2
	v_mfma_f32_16x16x32_bf16 v[110:113], v[82:85], v[178:181], v[110:113]
	s_add_u32 s79, s10, 0x80
	v_mfma_f32_16x16x32_bf16 v[94:97], v[102:105], v[178:181], v[94:97]
	s_addc_u32 s21, s11, 0
	v_mfma_f32_16x16x32_bf16 v[78:81], v[82:85], v[186:189], v[78:81]
	s_cmp_eq_u32 s68, s20
	v_mfma_f32_16x16x32_bf16 v[74:77], v[102:105], v[186:189], v[74:77]
	s_cselect_b32 s21, s59, s21
	v_mfma_f32_16x16x32_bf16 v[142:145], v[98:101], v[166:169], v[142:145]
	s_cselect_b32 s20, s58, s79
	v_mfma_f32_16x16x32_bf16 v[138:141], v[106:109], v[166:169], v[138:141]
	s_cselect_b32 s81, s61, s63
	v_mfma_f32_16x16x32_bf16 v[126:129], v[98:101], v[174:177], v[126:129]
	s_cselect_b32 s80, s60, s62
	v_mfma_f32_16x16x32_bf16 v[122:125], v[106:109], v[174:177], v[122:125]
	v_mfma_f32_16x16x32_bf16 v[110:113], v[98:101], v[182:185], v[110:113]
	v_mfma_f32_16x16x32_bf16 v[94:97], v[106:109], v[182:185], v[94:97]
	v_mfma_f32_16x16x32_bf16 v[78:81], v[98:101], v[190:193], v[78:81]
	v_mfma_f32_16x16x32_bf16 v[74:77], v[106:109], v[190:193], v[74:77]
	v_mfma_f32_16x16x32_bf16 v[134:137], v[146:149], v[162:165], v[134:137]
	v_mfma_f32_16x16x32_bf16 v[130:133], v[154:157], v[162:165], v[130:133]
	v_mfma_f32_16x16x32_bf16 v[118:121], v[146:149], v[170:173], v[118:121]
	v_mfma_f32_16x16x32_bf16 v[114:117], v[154:157], v[170:173], v[114:117]
	v_mfma_f32_16x16x32_bf16 v[90:93], v[146:149], v[178:181], v[90:93]
	v_mfma_f32_16x16x32_bf16 v[86:89], v[154:157], v[178:181], v[86:89]
	v_mfma_f32_16x16x32_bf16 v[70:73], v[146:149], v[186:189], v[70:73]
	v_mfma_f32_16x16x32_bf16 v[66:69], v[154:157], v[186:189], v[66:69]
	v_mfma_f32_16x16x32_bf16 v[134:137], v[150:153], v[166:169], v[134:137]
	v_mfma_f32_16x16x32_bf16 v[130:133], v[158:161], v[166:169], v[130:133]
	v_mfma_f32_16x16x32_bf16 v[118:121], v[150:153], v[174:177], v[118:121]
	v_mfma_f32_16x16x32_bf16 v[114:117], v[158:161], v[174:177], v[114:117]
	v_mfma_f32_16x16x32_bf16 v[90:93], v[150:153], v[182:185], v[90:93]
	v_mfma_f32_16x16x32_bf16 v[86:89], v[158:161], v[182:185], v[86:89]
	v_mfma_f32_16x16x32_bf16 v[70:73], v[150:153], v[190:193], v[70:73]
	v_mfma_f32_16x16x32_bf16 v[66:69], v[158:161], v[190:193], v[66:69]
	s_setprio 0
	s_barrier
	s_add_u32 s100, s80, s46
	s_addc_u32 s101, s81, s47
	s_add_i32 m0, s22, 0x10000
	ds_read_b128 v[162:165], v249 offset:16384
	global_load_lds_dwordx4 v0, s[80:81]
	s_add_i32 m0, s22, 0x12000
	ds_read_b128 v[166:169], v249 offset:17408
	global_load_lds_dwordx4 v218, s[80:81]
	s_add_i32 m0, s22, 0x14000
	ds_read_b128 v[170:173], v249 offset:18432
	global_load_lds_dwordx4 v0, s[100:101]
	s_add_i32 m0, s22, 0x16000
	ds_read_b128 v[174:177], v249 offset:19456
	global_load_lds_dwordx4 v218, s[100:101]
	s_mov_b32 m0, s64
	ds_read_b128 v[178:181], v249 offset:20480
	global_load_lds_dwordx4 v0, s[20:21]
	s_mov_b32 m0, s30
	ds_read_b128 v[182:185], v249 offset:21504
	global_load_lds_dwordx4 v218, s[20:21]
	ds_read_b128 v[186:189], v249 offset:22528
	ds_read_b128 v[190:193], v249 offset:23552
	s_waitcnt vmcnt(8) lgkmcnt(0)
	s_barrier
	s_setprio 1
	v_mfma_f32_16x16x32_bf16 v[62:65], v[82:85], v[162:165], v[62:65]
	v_mfma_f32_16x16x32_bf16 v[58:61], v[102:105], v[162:165], v[58:61]
	v_mfma_f32_16x16x32_bf16 v[46:49], v[82:85], v[170:173], v[46:49]
	v_mfma_f32_16x16x32_bf16 v[42:45], v[102:105], v[170:173], v[42:45]
	v_mfma_f32_16x16x32_bf16 v[30:33], v[82:85], v[178:181], v[30:33]
	v_mfma_f32_16x16x32_bf16 v[26:29], v[102:105], v[178:181], v[26:29]
	v_mfma_f32_16x16x32_bf16 v[14:17], v[82:85], v[186:189], v[14:17]
	v_mfma_f32_16x16x32_bf16 v[10:13], v[102:105], v[186:189], v[10:13]
	v_mfma_f32_16x16x32_bf16 v[62:65], v[98:101], v[166:169], v[62:65]
	v_mfma_f32_16x16x32_bf16 v[58:61], v[106:109], v[166:169], v[58:61]
	v_mfma_f32_16x16x32_bf16 v[46:49], v[98:101], v[174:177], v[46:49]
	v_mfma_f32_16x16x32_bf16 v[42:45], v[106:109], v[174:177], v[42:45]
	v_mfma_f32_16x16x32_bf16 v[30:33], v[98:101], v[182:185], v[30:33]
	v_mfma_f32_16x16x32_bf16 v[26:29], v[106:109], v[182:185], v[26:29]
	v_mfma_f32_16x16x32_bf16 v[14:17], v[98:101], v[190:193], v[14:17]
	v_mfma_f32_16x16x32_bf16 v[10:13], v[106:109], v[190:193], v[10:13]
	v_mfma_f32_16x16x32_bf16 v[54:57], v[146:149], v[162:165], v[54:57]
	v_mfma_f32_16x16x32_bf16 v[50:53], v[154:157], v[162:165], v[50:53]
	v_mfma_f32_16x16x32_bf16 v[38:41], v[146:149], v[170:173], v[38:41]
	v_mfma_f32_16x16x32_bf16 v[34:37], v[154:157], v[170:173], v[34:37]
	v_mfma_f32_16x16x32_bf16 v[22:25], v[146:149], v[178:181], v[22:25]
	v_mfma_f32_16x16x32_bf16 v[18:21], v[154:157], v[178:181], v[18:21]
	v_mfma_f32_16x16x32_bf16 v[6:9], v[146:149], v[186:189], v[6:9]
	v_mfma_f32_16x16x32_bf16 v[2:5], v[154:157], v[186:189], v[2:5]
	v_mfma_f32_16x16x32_bf16 v[54:57], v[150:153], v[166:169], v[54:57]
	v_mfma_f32_16x16x32_bf16 v[50:53], v[158:161], v[166:169], v[50:53]
	v_mfma_f32_16x16x32_bf16 v[38:41], v[150:153], v[174:177], v[38:41]
	v_mfma_f32_16x16x32_bf16 v[34:37], v[158:161], v[174:177], v[34:37]
	v_mfma_f32_16x16x32_bf16 v[22:25], v[150:153], v[182:185], v[22:25]
	v_mfma_f32_16x16x32_bf16 v[18:21], v[158:161], v[182:185], v[18:21]
	v_mfma_f32_16x16x32_bf16 v[6:9], v[150:153], v[190:193], v[6:9]
	v_mfma_f32_16x16x32_bf16 v[2:5], v[158:161], v[190:193], v[2:5]
	s_setprio 0
	s_barrier
; #define PG8_STAGE(bufoff, gbase, voff) do { _Pragma("unroll") for (int _i = 0; _i < 2; ++_i) \
;         __builtin_amdgcn_global_load_lds((const unsigned*)((const char*)(gbase) + (voff)[_i]), (PG8_LAS unsigned*)(lds + (bufoff) + ldsw + _i * 8192), 16, 0, 0); } while (0)
; #define PG8_LDA(dst, b, h) do { _Pragma("unroll") for (int m = 0; m < 4; ++m) _Pragma("unroll") for (int k = 0; k < 2; ++k) dst[m][k] = *(const PG8_LAS bf16x8*)(lds + PG8_SA(b, h) + aoff + m * 2048 + k * 1024); } while (0)
; #define PG8_LDB(dst, b, h) do { _Pragma("unroll") for (int n = 0; n < 2; ++n) _Pragma("unroll") for (int k = 0; k < 2; ++k) dst[n][k] = *(const PG8_LAS bf16x8*)(lds + PG8_SB(b, h) + boff + n * 2048 + k * 1024); } while (0)
; #define PG8_MMA(ai, bj, At, Bt) do { __builtin_amdgcn_s_setprio(1); _Pragma("unroll") for (int m = 0; m < 4; ++m) _Pragma("unroll") for (int n = 0; n < 2; ++n) _Pragma("unroll") for (int k = 0; k < 2; ++k) \
;         acc[ai][bj][m][n] = __builtin_amdgcn_mfma_f32_16x16x32_bf16(Bt[n][k], At[m][k], acc[ai][bj][m][n], 0, 0, 0); __builtin_amdgcn_s_setprio(0); } while (0)
; #define PG8_WAIT_V(n) asm volatile("s_waitcnt vmcnt(" #n ")" ::: "memory")
; #define PG8_WAIT_L(n) asm volatile("s_waitcnt lgkmcnt(" #n ")" ::: "memory")
; #define PG8_BAR __builtin_amdgcn_s_barrier()
; #define PG8_SCHED __builtin_amdgcn_sched_barrier(0)
; template <class Epi, class Sched, bool ALIGN_EPI = false, bool SP2 = false>
; __device__ __forceinline__ void gemm_phase(PG8_LAS unsigned char* lds, const Gemm g, const Sched& S, const Epi& E) {
;     ...
;             PG8_LDB(B0, 1, 0); PG8_LDB(B1, 1, 1); PG8_SCHED; PG8_LDA(At, 1, 0); PG8_STAGE(PG8_SA(0, 1), a2 + hstep, voffA);
;             PG8_WAIT_V(8); PG8_WAIT_L(0); PG8_BAR; PG8_MMA(0, 0, At, B0); PG8_MMA(0, 1, At, B1); PG8_BAR; PG8_SCHED;
;             PG8_LDA(At, 1, 1); PG8_STAGE(PG8_SB(1, 0), b3, voffB); PG8_STAGE(PG8_SB(1, 1), b3 + hstep, voffB); PG8_STAGE(PG8_SA(1, 0), a3, voffA);
;             PG8_WAIT_V(8); PG8_WAIT_L(0); PG8_BAR; PG8_MMA(1, 0, At, B0); PG8_MMA(1, 1, At, B1); PG8_BAR; PG8_SCHED;
	s_mov_b32 m0, s31
	ds_read_b128 v[82:85], v246 offset:32768
	global_load_lds_dwordx4 v224, s[20:21]
	s_mov_b32 m0, s33
	ds_read_b128 v[98:101], v246 offset:33792
	global_load_lds_dwordx4 v226, s[20:21]
	ds_read_b128 v[102:105], v246 offset:34816
	ds_read_b128 v[106:109], v246 offset:35840
	ds_read_b128 v[146:149], v246 offset:49152
	ds_read_b128 v[150:153], v246 offset:50176
	ds_read_b128 v[154:157], v246 offset:51200
	ds_read_b128 v[158:161], v246 offset:52224
	ds_read_b128 v[162:165], v249 offset:32768
	ds_read_b128 v[166:169], v249 offset:33792
	ds_read_b128 v[170:173], v249 offset:34816
	ds_read_b128 v[174:177], v249 offset:35840
	ds_read_b128 v[178:181], v249 offset:36864
	ds_read_b128 v[182:185], v249 offset:37888
	ds_read_b128 v[186:189], v249 offset:38912
	ds_read_b128 v[190:193], v249 offset:39936
	s_waitcnt vmcnt(8) lgkmcnt(0)
	s_barrier
	s_setprio 1
	v_mfma_f32_16x16x32_bf16 v[142:145], v[82:85], v[162:165], v[142:145]
	v_mfma_f32_16x16x32_bf16 v[138:141], v[102:105], v[162:165], v[138:141]
	v_mfma_f32_16x16x32_bf16 v[126:129], v[82:85], v[170:173], v[126:129]
	v_mfma_f32_16x16x32_bf16 v[122:125], v[102:105], v[170:173], v[122:125]
	v_mfma_f32_16x16x32_bf16 v[110:113], v[82:85], v[178:181], v[110:113]
	v_mfma_f32_16x16x32_bf16 v[94:97], v[102:105], v[178:181], v[94:97]
	v_mfma_f32_16x16x32_bf16 v[78:81], v[82:85], v[186:189], v[78:81]
	v_mfma_f32_16x16x32_bf16 v[74:77], v[102:105], v[186:189], v[74:77]
	v_mfma_f32_16x16x32_bf16 v[142:145], v[98:101], v[166:169], v[142:145]
	v_mfma_f32_16x16x32_bf16 v[138:141], v[106:109], v[166:169], v[138:141]
	v_mfma_f32_16x16x32_bf16 v[126:129], v[98:101], v[174:177], v[126:129]
	v_mfma_f32_16x16x32_bf16 v[122:125], v[106:109], v[174:177], v[122:125]
	v_mfma_f32_16x16x32_bf16 v[110:113], v[98:101], v[182:185], v[110:113]
	v_mfma_f32_16x16x32_bf16 v[94:97], v[106:109], v[182:185], v[94:97]
	v_mfma_f32_16x16x32_bf16 v[78:81], v[98:101], v[190:193], v[78:81]
	v_mfma_f32_16x16x32_bf16 v[74:77], v[106:109], v[190:193], v[74:77]
	v_mfma_f32_16x16x32_bf16 v[134:137], v[146:149], v[162:165], v[134:137]
	v_mfma_f32_16x16x32_bf16 v[130:133], v[154:157], v[162:165], v[130:133]
	v_mfma_f32_16x16x32_bf16 v[118:121], v[146:149], v[170:173], v[118:121]
	v_mfma_f32_16x16x32_bf16 v[114:117], v[154:157], v[170:173], v[114:117]
	v_mfma_f32_16x16x32_bf16 v[90:93], v[146:149], v[178:181], v[90:93]
	v_mfma_f32_16x16x32_bf16 v[86:89], v[154:157], v[178:181], v[86:89]
	v_mfma_f32_16x16x32_bf16 v[70:73], v[146:149], v[186:189], v[70:73]
	v_mfma_f32_16x16x32_bf16 v[66:69], v[154:157], v[186:189], v[66:69]
	v_mfma_f32_16x16x32_bf16 v[134:137], v[150:153], v[166:169], v[134:137]
	v_mfma_f32_16x16x32_bf16 v[130:133], v[158:161], v[166:169], v[130:133]
	v_mfma_f32_16x16x32_bf16 v[118:121], v[150:153], v[174:177], v[118:121]
	v_mfma_f32_16x16x32_bf16 v[114:117], v[158:161], v[174:177], v[114:117]
	v_mfma_f32_16x16x32_bf16 v[90:93], v[150:153], v[182:185], v[90:93]
	v_mfma_f32_16x16x32_bf16 v[86:89], v[158:161], v[182:185], v[86:89]
	v_mfma_f32_16x16x32_bf16 v[70:73], v[150:153], v[190:193], v[70:73]
	v_mfma_f32_16x16x32_bf16 v[66:69], v[158:161], v[190:193], v[66:69]
	s_setprio 0
	s_barrier
	s_add_i32 m0, s22, 0x17f80
	ds_read_b128 v[162:165], v249 offset:49152
	global_load_lds_dwordx4 v0, s[80:81] offset:128
	s_add_i32 m0, s22, 0x19f80
	ds_read_b128 v[166:169], v249 offset:50176
	global_load_lds_dwordx4 v218, s[80:81] offset:128
	s_add_i32 m0, s22, 0x1bf80
	ds_read_b128 v[170:173], v249 offset:51200
	global_load_lds_dwordx4 v0, s[100:101] offset:128
	s_add_i32 m0, s22, 0x1df80
	ds_read_b128 v[174:177], v249 offset:52224
	global_load_lds_dwordx4 v218, s[100:101] offset:128
	s_sub_i32 m0, s39, 0x80
	ds_read_b128 v[178:181], v249 offset:53248
	global_load_lds_dwordx4 v0, s[20:21] offset:128
	s_sub_i32 m0, s65, 0x80
	ds_read_b128 v[182:185], v249 offset:54272
	global_load_lds_dwordx4 v218, s[20:21] offset:128
	ds_read_b128 v[186:189], v249 offset:55296
	ds_read_b128 v[190:193], v249 offset:56320
	s_waitcnt vmcnt(8) lgkmcnt(0)
	s_barrier
	s_setprio 1
	v_mfma_f32_16x16x32_bf16 v[62:65], v[82:85], v[162:165], v[62:65]
	v_mfma_f32_16x16x32_bf16 v[58:61], v[102:105], v[162:165], v[58:61]
	v_mfma_f32_16x16x32_bf16 v[46:49], v[82:85], v[170:173], v[46:49]
	v_mfma_f32_16x16x32_bf16 v[42:45], v[102:105], v[170:173], v[42:45]
	s_add_u32 s10, s10, 0x100
	v_mfma_f32_16x16x32_bf16 v[30:33], v[82:85], v[178:181], v[30:33]
	s_addc_u32 s11, s11, 0
	v_mfma_f32_16x16x32_bf16 v[26:29], v[102:105], v[178:181], v[26:29]
	s_add_u32 s62, s62, 0x100
	v_mfma_f32_16x16x32_bf16 v[14:17], v[82:85], v[186:189], v[14:17]
	s_addc_u32 s63, s63, 0
	v_mfma_f32_16x16x32_bf16 v[10:13], v[102:105], v[186:189], v[10:13]
	s_mov_b32 s20, s78
	v_mfma_f32_16x16x32_bf16 v[62:65], v[98:101], v[166:169], v[62:65]
	v_mfma_f32_16x16x32_bf16 v[58:61], v[106:109], v[166:169], v[58:61]
	v_mfma_f32_16x16x32_bf16 v[46:49], v[98:101], v[174:177], v[46:49]
	v_mfma_f32_16x16x32_bf16 v[42:45], v[106:109], v[174:177], v[42:45]
	v_mfma_f32_16x16x32_bf16 v[30:33], v[98:101], v[182:185], v[30:33]
	v_mfma_f32_16x16x32_bf16 v[26:29], v[106:109], v[182:185], v[26:29]
	v_mfma_f32_16x16x32_bf16 v[14:17], v[98:101], v[190:193], v[14:17]
	v_mfma_f32_16x16x32_bf16 v[10:13], v[106:109], v[190:193], v[10:13]
	v_mfma_f32_16x16x32_bf16 v[54:57], v[146:149], v[162:165], v[54:57]
	v_mfma_f32_16x16x32_bf16 v[50:53], v[154:157], v[162:165], v[50:53]
	v_mfma_f32_16x16x32_bf16 v[38:41], v[146:149], v[170:173], v[38:41]
	v_mfma_f32_16x16x32_bf16 v[34:37], v[154:157], v[170:173], v[34:37]
	v_mfma_f32_16x16x32_bf16 v[22:25], v[146:149], v[178:181], v[22:25]
	v_mfma_f32_16x16x32_bf16 v[18:21], v[154:157], v[178:181], v[18:21]
	v_mfma_f32_16x16x32_bf16 v[6:9], v[146:149], v[186:189], v[6:9]
	v_mfma_f32_16x16x32_bf16 v[2:5], v[154:157], v[186:189], v[2:5]
	v_mfma_f32_16x16x32_bf16 v[54:57], v[150:153], v[166:169], v[54:57]
	v_mfma_f32_16x16x32_bf16 v[50:53], v[158:161], v[166:169], v[50:53]
	v_mfma_f32_16x16x32_bf16 v[38:41], v[150:153], v[174:177], v[38:41]
	v_mfma_f32_16x16x32_bf16 v[34:37], v[158:161], v[174:177], v[34:37]
	v_mfma_f32_16x16x32_bf16 v[22:25], v[150:153], v[182:185], v[22:25]
	v_mfma_f32_16x16x32_bf16 v[18:21], v[158:161], v[182:185], v[18:21]
	v_mfma_f32_16x16x32_bf16 v[6:9], v[150:153], v[190:193], v[6:9]
	v_mfma_f32_16x16x32_bf16 v[2:5], v[158:161], v[190:193], v[2:5]
	s_setprio 0
	s_barrier
	s_cmp_ge_i32 s78, s67
	s_cbranch_scc0 .LBB0_570
